# speedup vs baseline: 1.0711x; 1.0292x over previous
; __device__ __forceinline__ void dtile_load(u32x4 (&kr)[2], u32x4 (&vr)[2], const bf16* __restrict__ Kg, const bf16* __restrict__ Vg, int vts, int kt  , int part, int tidx) {
; #pragma unroll
;   for (int i = 0; i < 2; ++i) {
;     const int c = tidx + (2 * part + i) * NTHR;
;     kr[i] = *reinterpret_cast<const u32x4*>(Kg + (size_t)(kt * 128 + (c >> 4)) * 1024 + (c & 15) * 8);
;     vr[i] = *reinterpret_cast<const u32x4*>(Vg + (size_t)(c >> 4) * vts + kt * 128 + (c & 15) * 8);
;   }
; }
; __device__ __forceinline__ void attn_diff(const bf16* __restrict__ Qg, const bf16* __restrict__ Kg, const bf16* __restrict__ Vg, int vts, ...
;     ...
;   for (int it = 0; it < nit; ++it) {
;     const int kt2 = kt_hi - 1 - it;
;     const char* bufc = lds + (it & 1) * ATT_BUF;
;     char* bufn = lds + ((it + 1) & 1) * ATT_BUF;
;     const bool more = it + 1 < nit;
;     if (more) dtile_load(kr, vr, Kg, Vg, vts, kt2 - 1, 0, tidx);
.LBB0_216:
	v_cmp_ne_u32_e32 vcc, s86, v236
	s_or_b64 s[94:95], s[94:95], exec
	s_and_saveexec_b64 s[82:83], vcc
	s_cbranch_execz .LBB0_215
	v_subrev_u32_e32 v5, s86, v226
	s_add_i32 s97, s86, 1
	v_cmp_lt_i32_e64 s[10:11], s97, v232
	v_cmp_ge_i32_e32 vcc, s97, v232
	v_lshlrev_b32_e32 v3, 7, v5
	s_and_saveexec_b64 s[0:1], vcc
	s_xor_b64 s[0:1], exec, s[0:1]
	v_lshlrev_b32_e32 v3, 7, v5
	v_add_u32_e32 v10, 0xffffff80, v3
	v_ashrrev_i32_e32 v11, 31, v10
	s_andn2_saveexec_b64 s[0:1], s[0:1]
	s_cbranch_execz .LBB0_221
	v_add_u32_e32 v10, 0xffffff80, v3
	v_add_u32_e32 v8, v10, v227
	v_ashrrev_i32_e32 v9, 31, v8
	v_ashrrev_i32_e32 v11, 31, v10
	v_lshlrev_b64 v[8:9], 11, v[8:9]
	v_lshl_add_u64 v[6:7], v[10:11], 1, v[172:173]
	v_lshl_add_u64 v[8:9], v[158:159], 0, v[8:9]
	global_load_dwordx4 v[128:131], v[8:9], off
	v_lshl_add_u64 v[8:9], v[160:161], 1, v[6:7]
	v_lshl_add_u64 v[6:7], v[162:163], 1, v[6:7]
	global_load_dwordx4 v[132:135], v[8:9], off
	global_load_dwordx4 v[140:143], v[6:7], off
	v_add_u32_e32 v8, v10, v228
	v_ashrrev_i32_e32 v9, 31, v8
	v_lshlrev_b64 v[8:9], 11, v[8:9]
	v_lshl_add_u64 v[8:9], v[158:159], 0, v[8:9]
	global_load_dwordx4 v[136:139], v[8:9], off

.LBB0_223:
	s_and_saveexec_b64 s[90:91], s[0:1]
	s_cbranch_execz .LBB0_231
	v_cmp_lt_i32_e32 vcc, v144, v231
	s_and_saveexec_b64 s[88:89], vcc
	s_cbranch_execz .LBB0_230
	v_add_u32_e32 v0, v15, v152
	ds_read_b128 v[176:179], v0
	ds_read_b128 v[180:183], v0 offset:8704
	ds_read_b128 v[184:187], v0 offset:32
	ds_read_b128 v[196:199], v0 offset:8736
	ds_read_b128 v[200:203], v0 offset:64
	ds_read_b128 v[204:207], v0 offset:8768
	ds_read_b128 v[244:247], v0 offset:96
	ds_read_b128 v[248:251], v0 offset:8800
	v_cmp_gt_i32_e32 vcc, 59, v242
	s_cbranch_vccnz .Lmy_bias_gen
	v_cvt_f32_i32_e32 v0, v242
	v_mul_f32_e32 v188, -2.0, v168
	v_fma_f32 v80, v168, v0, -v2
	v_mul_f32_e32 v0, 0xc1000000, v168
	v_sub_f32_e32 v81, v80, v168
	s_nop 0
	v_pk_add_f32 v[84:85], v[80:81], v[0:1] op_sel_hi:[1,0]
	v_mul_f32_e32 v0, 0xc1800000, v168
	v_pk_add_f32 v[82:83], v[80:81], v[188:189] op_sel_hi:[1,0]
	v_pk_add_f32 v[88:89], v[80:81], v[0:1] op_sel_hi:[1,0]
	v_pk_add_f32 v[92:93], v[84:85], v[0:1] op_sel_hi:[1,0]
	v_mul_f32_e32 v0, 0xc2000000, v168
	v_pk_add_f32 v[86:87], v[84:85], v[188:189] op_sel_hi:[1,0]
	v_pk_add_f32 v[96:97], v[80:81], v[0:1] op_sel_hi:[1,0]
	v_pk_add_f32 v[100:101], v[84:85], v[0:1] op_sel_hi:[1,0]
	v_pk_add_f32 v[104:105], v[88:89], v[0:1] op_sel_hi:[1,0]
	v_pk_add_f32 v[108:109], v[92:93], v[0:1] op_sel_hi:[1,0]
	v_pk_add_f32 v[90:91], v[88:89], v[188:189] op_sel_hi:[1,0]
	v_pk_add_f32 v[94:95], v[92:93], v[188:189] op_sel_hi:[1,0]
	v_pk_add_f32 v[98:99], v[96:97], v[188:189] op_sel_hi:[1,0]
	v_pk_add_f32 v[102:103], v[100:101], v[188:189] op_sel_hi:[1,0]
	v_pk_add_f32 v[106:107], v[104:105], v[188:189] op_sel_hi:[1,0]
	v_pk_add_f32 v[110:111], v[108:109], v[188:189] op_sel_hi:[1,0]
	s_branch .Lmy_bias_done
.Lmy_bias_gen:
	v_cvt_f32_i32_e32 v0, v242
	s_mov_b32 s12, 0
	s_mov_b32 s13, -1.0
	v_pk_add_f32 v[80:81], v[0:1], s[12:13] op_sel_hi:[0,1]
	s_mov_b32 s12, -2.0
	s_mov_b32 s13, 0xc0400000
	v_pk_add_f32 v[82:83], v[0:1], s[12:13] op_sel_hi:[0,1]
	s_mov_b32 s12, 0xc1000000
	s_mov_b32 s13, 0xc1100000
	v_pk_add_f32 v[84:85], v[0:1], s[12:13] op_sel_hi:[0,1]
	s_mov_b32 s12, 0xc1200000
	s_mov_b32 s13, 0xc1300000
	v_pk_add_f32 v[86:87], v[0:1], s[12:13] op_sel_hi:[0,1]
	s_mov_b32 s12, 0xc1800000
	s_mov_b32 s13, 0xc1880000
	v_pk_add_f32 v[88:89], v[0:1], s[12:13] op_sel_hi:[0,1]
	s_mov_b32 s12, 0xc1900000
	s_mov_b32 s13, 0xc1980000
	v_pk_add_f32 v[90:91], v[0:1], s[12:13] op_sel_hi:[0,1]
	s_mov_b32 s12, 0xc1c00000
	s_mov_b32 s13, 0xc1c80000
	v_pk_add_f32 v[92:93], v[0:1], s[12:13] op_sel_hi:[0,1]
	s_mov_b32 s12, 0xc1d00000
	s_mov_b32 s13, 0xc1d80000
	v_pk_add_f32 v[94:95], v[0:1], s[12:13] op_sel_hi:[0,1]
	v_pk_add_f32 v[96:97], v[0:1], s[92:93] op_sel_hi:[0,1]
	v_pk_add_f32 v[98:99], v[0:1], s[42:43] op_sel_hi:[0,1]
	v_pk_add_f32 v[100:101], v[0:1], s[80:81] op_sel_hi:[0,1]
	s_mov_b32 s12, 0xc2280000
	s_mov_b32 s13, 0xc22c0000
	v_pk_add_f32 v[102:103], v[0:1], s[12:13] op_sel_hi:[0,1]
	s_mov_b32 s12, 0xc2400000
	s_mov_b32 s13, 0xc2440000
	v_pk_add_f32 v[104:105], v[0:1], s[12:13] op_sel_hi:[0,1]
	s_mov_b32 s12, 0xc2480000
	s_mov_b32 s13, 0xc24c0000
	v_pk_add_f32 v[106:107], v[0:1], s[12:13] op_sel_hi:[0,1]
	s_mov_b32 s12, 0xc2600000
	s_mov_b32 s13, 0xc2640000
	v_pk_add_f32 v[108:109], v[0:1], s[12:13] op_sel_hi:[0,1]
	s_mov_b32 s12, 0xc2680000
	s_mov_b32 s13, 0xc26c0000
	v_pk_add_f32 v[110:111], v[0:1], s[12:13] op_sel_hi:[0,1]
	v_fma_f32 v80, v168, |v80|, -v2
	v_fma_f32 v81, v168, |v81|, -v2
	v_fma_f32 v82, v168, |v82|, -v2
	v_fma_f32 v83, v168, |v83|, -v2
	v_fma_f32 v84, v168, |v84|, -v2
	v_fma_f32 v85, v168, |v85|, -v2
	v_fma_f32 v86, v168, |v86|, -v2
	v_fma_f32 v87, v168, |v87|, -v2
	v_fma_f32 v88, v168, |v88|, -v2
	v_fma_f32 v89, v168, |v89|, -v2
	v_fma_f32 v90, v168, |v90|, -v2
	v_fma_f32 v91, v168, |v91|, -v2
	v_fma_f32 v92, v168, |v92|, -v2
	v_fma_f32 v93, v168, |v93|, -v2
	v_fma_f32 v94, v168, |v94|, -v2
	v_fma_f32 v95, v168, |v95|, -v2
	v_fma_f32 v96, v168, |v96|, -v2
	v_fma_f32 v97, v168, |v97|, -v2
	v_fma_f32 v98, v168, |v98|, -v2
	v_fma_f32 v99, v168, |v99|, -v2
	v_fma_f32 v100, v168, |v100|, -v2
	v_fma_f32 v101, v168, |v101|, -v2
	v_fma_f32 v102, v168, |v102|, -v2
	v_fma_f32 v103, v168, |v103|, -v2
	v_fma_f32 v104, v168, |v104|, -v2
	v_fma_f32 v105, v168, |v105|, -v2
	v_fma_f32 v106, v168, |v106|, -v2
	v_fma_f32 v107, v168, |v107|, -v2
	v_fma_f32 v108, v168, |v108|, -v2
	v_fma_f32 v109, v168, |v109|, -v2
	v_fma_f32 v110, v168, |v110|, -v2
	v_fma_f32 v111, v168, |v111|, -v2
.Lmy_bias_done:
	s_nop 1
	s_waitcnt lgkmcnt(7)
	v_mfma_f32_32x32x16_bf16 v[80:95], v[176:179], v[112:115], v[80:95]
	s_waitcnt lgkmcnt(6)
	v_mfma_f32_32x32x16_bf16 v[96:111], v[180:183], v[112:115], v[96:111]
	s_waitcnt lgkmcnt(5)
	v_mfma_f32_32x32x16_bf16 v[80:95], v[184:187], v[116:119], v[80:95]
	s_waitcnt lgkmcnt(4)
	v_mfma_f32_32x32x16_bf16 v[96:111], v[196:199], v[116:119], v[96:111]
	s_waitcnt lgkmcnt(3)
	v_mfma_f32_32x32x16_bf16 v[80:95], v[200:203], v[120:123], v[80:95]
	s_waitcnt lgkmcnt(2)
	v_mfma_f32_32x32x16_bf16 v[96:111], v[204:207], v[120:123], v[96:111]
	s_waitcnt lgkmcnt(1)
	v_mfma_f32_32x32x16_bf16 v[80:95], v[244:247], v[124:127], v[80:95]
	s_waitcnt lgkmcnt(0)
	v_mfma_f32_32x32x16_bf16 v[96:111], v[248:251], v[124:127], v[96:111]
	v_add_u32_e32 v0, v14, v152
	ds_read_b128 v[176:179], v0
	ds_read_b128 v[180:183], v0 offset:32
	ds_read_b128 v[184:187], v0 offset:64
	ds_read_b128 v[196:199], v0 offset:96
	ds_read_b128 v[200:203], v0 offset:8704
	ds_read_b128 v[204:207], v0 offset:8736
	ds_read_b128 v[244:247], v0 offset:8768
	ds_read_b128 v[248:251], v0 offset:8800
	v_cmp_gt_i32_e32 vcc, v144, v233
	s_and_saveexec_b64 s[98:99], vcc
	s_cbranch_execz .LBB0_227
	v_cmp_lt_i32_e64 s[72:73], 26, v243
	v_cmp_lt_i32_e64 s[74:75], 27, v243
	v_cmp_lt_i32_e64 s[70:71], 25, v243
	s_or_b64 s[72:73], s[74:75], s[72:73]
	v_cmp_lt_i32_e64 s[68:69], 24, v243
	s_or_b64 s[70:71], s[72:73], s[70:71]
	v_cmp_lt_i32_e64 s[66:67], 19, v243
	s_or_b64 s[68:69], s[70:71], s[68:69]
	v_cmp_lt_i32_e64 s[64:65], 18, v243
	s_or_b64 s[66:67], s[68:69], s[66:67]
	v_cmp_lt_i32_e64 s[62:63], 17, v243
	s_or_b64 s[64:65], s[66:67], s[64:65]
	v_cmp_lt_i32_e64 s[60:61], 16, v243
	s_or_b64 s[62:63], s[64:65], s[62:63]
	v_cmp_lt_i32_e64 s[58:59], 11, v243
	s_or_b64 s[60:61], s[62:63], s[60:61]
	v_cmp_lt_i32_e64 s[56:57], 10, v243
	s_or_b64 s[58:59], s[60:61], s[58:59]
	v_cmp_lt_i32_e64 s[54:55], 9, v243
	s_or_b64 s[56:57], s[58:59], s[56:57]
	v_cmp_lt_i32_e64 s[52:53], 8, v243
	s_or_b64 s[54:55], s[56:57], s[54:55]
	v_cmp_lt_i32_e64 s[50:51], 3, v243
	s_or_b64 s[52:53], s[54:55], s[52:53]
	v_cmp_lt_i32_e64 s[48:49], 2, v243
	s_or_b64 s[50:51], s[52:53], s[50:51]
	v_cmp_lt_i32_e64 s[46:47], 1, v243
	s_or_b64 s[48:49], s[50:51], s[48:49]
	v_cmp_lt_i32_e64 s[44:45], 0, v243
	s_or_b64 s[46:47], s[48:49], s[46:47]
	s_or_b64 s[44:45], s[46:47], s[44:45]
	v_cmp_lt_i32_e64 s[40:41], 58, v243
	v_cndmask_b32_e64 v80, v209, v80, s[44:45]
	v_cmp_lt_i32_e64 s[44:45], 59, v243
	v_cmp_lt_i32_e64 s[38:39], 57, v243
	s_or_b64 s[40:41], s[44:45], s[40:41]
	v_cmp_lt_i32_e64 s[36:37], 56, v243
	s_or_b64 s[38:39], s[40:41], s[38:39]
	v_cmp_lt_i32_e64 s[34:35], 51, v243
	s_or_b64 s[36:37], s[38:39], s[36:37]
	v_cmp_lt_i32_e64 s[30:31], 50, v243
	s_or_b64 s[34:35], s[36:37], s[34:35]
	v_cmp_lt_i32_e64 s[28:29], 49, v243
	s_or_b64 s[30:31], s[34:35], s[30:31]
	v_cmp_lt_i32_e64 s[26:27], 48, v243
	s_or_b64 s[28:29], s[30:31], s[28:29]
	v_cmp_lt_i32_e64 s[24:25], 43, v243
	s_or_b64 s[26:27], s[28:29], s[26:27]
	v_cmp_lt_i32_e64 s[22:23], 42, v243
	s_or_b64 s[24:25], s[26:27], s[24:25]
	v_cmp_lt_i32_e64 s[20:21], 41, v243
	s_or_b64 s[22:23], s[24:25], s[22:23]
	v_cmp_lt_i32_e64 s[18:19], 40, v243
	s_or_b64 s[20:21], s[22:23], s[20:21]
	v_cmp_lt_i32_e64 s[16:17], 35, v243
	s_or_b64 s[18:19], s[20:21], s[18:19]
	v_cmp_lt_i32_e64 s[14:15], 34, v243
	s_or_b64 s[16:17], s[18:19], s[16:17]
	v_cmp_lt_i32_e64 s[12:13], 33, v243
	s_or_b64 s[14:15], s[16:17], s[14:15]
	v_cmp_lt_i32_e32 vcc, 32, v243
	s_or_b64 s[12:13], s[14:15], s[12:13]
	s_or_b64 vcc, s[12:13], vcc
	v_cndmask_b32_e64 v95, v209, v95, s[74:75]
	v_cndmask_b32_e64 v94, v209, v94, s[72:73]
	v_cndmask_b32_e64 v93, v209, v93, s[70:71]
	v_cndmask_b32_e64 v92, v209, v92, s[68:69]
	v_cndmask_b32_e64 v91, v209, v91, s[66:67]
	v_cndmask_b32_e64 v90, v209, v90, s[64:65]
	v_cndmask_b32_e64 v89, v209, v89, s[62:63]
	v_cndmask_b32_e64 v88, v209, v88, s[60:61]
	v_cndmask_b32_e64 v87, v209, v87, s[58:59]
	v_cndmask_b32_e64 v86, v209, v86, s[56:57]
	v_cndmask_b32_e64 v85, v209, v85, s[54:55]
	v_cndmask_b32_e64 v84, v209, v84, s[52:53]
	v_cndmask_b32_e64 v83, v209, v83, s[50:51]
	s_movk_i32 s51, 0x7fff
	s_movk_i32 s50, 0x1080
	v_cndmask_b32_e64 v82, v209, v82, s[48:49]
	s_mov_b32 s49, 0xee00000
	s_mov_b32 s3, s2
	s_mov_b32 s48, s85
	v_cndmask_b32_e64 v81, v209, v81, s[46:47]
	v_cndmask_b32_e64 v111, v209, v111, s[44:45]
	v_cndmask_b32_e64 v110, v209, v110, s[40:41]
	v_cndmask_b32_e64 v109, v209, v109, s[38:39]
	v_cndmask_b32_e64 v108, v209, v108, s[36:37]
	v_cndmask_b32_e64 v107, v209, v107, s[34:35]
	v_cndmask_b32_e64 v106, v209, v106, s[30:31]
	v_cndmask_b32_e64 v105, v209, v105, s[28:29]
	v_cndmask_b32_e64 v104, v209, v104, s[26:27]
	v_cndmask_b32_e64 v103, v209, v103, s[24:25]
	v_cndmask_b32_e64 v102, v209, v102, s[22:23]
	v_cndmask_b32_e64 v101, v209, v101, s[20:21]
	v_cndmask_b32_e64 v100, v209, v100, s[18:19]
	v_cndmask_b32_e64 v99, v209, v99, s[16:17]
	v_cndmask_b32_e64 v98, v209, v98, s[14:15]
	v_cndmask_b32_e64 v97, v209, v97, s[12:13]
	v_cndmask_b32_e32 v96, v209, v96, vcc
.LBB0_227:
	s_or_b64 exec, exec, s[98:99]
	s_nop 1
	v_max3_f32 v0, v80, v81, v82
	v_max3_f32 v188, v83, v84, v85
	v_max3_f32 v0, v0, v86, v87
	v_max3_f32 v188, v188, v88, v89
	v_max3_f32 v0, v0, v90, v91
	v_max3_f32 v188, v188, v92, v93
	v_max3_f32 v0, v0, v94, v95
	v_max3_f32 v188, v188, v96, v97
	v_max3_f32 v0, v0, v98, v99
	v_max3_f32 v188, v188, v100, v101
	v_max3_f32 v0, v0, v102, v103
	v_max3_f32 v188, v188, v104, v105
	v_max3_f32 v0, v0, v106, v107
	v_max3_f32 v188, v188, v108, v109
	v_max3_f32 v0, v0, v110, v111
	v_max_f32_e32 v0, v0, v188
	v_mov_b32_e32 v188, v0
	s_nop 1
	v_permlane32_swap_b32_e32 v0, v188
	v_max_f32_e32 v0, v0, v188
	s_mov_b32 s12, 0x41000000
	v_cmp_lt_f32_e32 vcc, s12, v0
	s_cbranch_vccz .LBB0_229
	v_max_f32_e32 v0, 0, v0
	v_exp_f32_e64 v188, -v0
	s_nop 0
	v_pk_mul_f32 v[78:79], v[78:79], v[188:189] op_sel_hi:[1,0]
	v_pk_mul_f32 v[76:77], v[76:77], v[188:189] op_sel_hi:[1,0]
	v_pk_mul_f32 v[74:75], v[74:75], v[188:189] op_sel_hi:[1,0]
	v_pk_mul_f32 v[72:73], v[72:73], v[188:189] op_sel_hi:[1,0]
	v_pk_mul_f32 v[70:71], v[70:71], v[188:189] op_sel_hi:[1,0]
	v_pk_mul_f32 v[68:69], v[68:69], v[188:189] op_sel_hi:[1,0]
	v_pk_mul_f32 v[66:67], v[66:67], v[188:189] op_sel_hi:[1,0]
	v_pk_mul_f32 v[64:65], v[64:65], v[188:189] op_sel_hi:[1,0]
	v_pk_mul_f32 v[62:63], v[62:63], v[188:189] op_sel_hi:[1,0]
	v_pk_mul_f32 v[60:61], v[60:61], v[188:189] op_sel_hi:[1,0]
	v_pk_mul_f32 v[58:59], v[58:59], v[188:189] op_sel_hi:[1,0]
	v_pk_mul_f32 v[56:57], v[56:57], v[188:189] op_sel_hi:[1,0]
	v_pk_mul_f32 v[54:55], v[54:55], v[188:189] op_sel_hi:[1,0]
	v_pk_mul_f32 v[52:53], v[52:53], v[188:189] op_sel_hi:[1,0]
	v_pk_mul_f32 v[50:51], v[50:51], v[188:189] op_sel_hi:[1,0]
	v_pk_mul_f32 v[48:49], v[48:49], v[188:189] op_sel_hi:[1,0]
	v_pk_mul_f32 v[46:47], v[46:47], v[188:189] op_sel_hi:[1,0]
	v_pk_mul_f32 v[44:45], v[44:45], v[188:189] op_sel_hi:[1,0]
	v_pk_mul_f32 v[42:43], v[42:43], v[188:189] op_sel_hi:[1,0]
	v_pk_mul_f32 v[40:41], v[40:41], v[188:189] op_sel_hi:[1,0]
	v_pk_mul_f32 v[38:39], v[38:39], v[188:189] op_sel_hi:[1,0]
	v_pk_mul_f32 v[36:37], v[36:37], v[188:189] op_sel_hi:[1,0]
	v_pk_mul_f32 v[34:35], v[34:35], v[188:189] op_sel_hi:[1,0]
	v_pk_mul_f32 v[32:33], v[32:33], v[188:189] op_sel_hi:[1,0]
	v_pk_mul_f32 v[30:31], v[30:31], v[188:189] op_sel_hi:[1,0]
	v_pk_mul_f32 v[28:29], v[28:29], v[188:189] op_sel_hi:[1,0]
	v_pk_mul_f32 v[26:27], v[26:27], v[188:189] op_sel_hi:[1,0]
	v_pk_mul_f32 v[24:25], v[24:25], v[188:189] op_sel_hi:[1,0]
	v_pk_mul_f32 v[22:23], v[22:23], v[188:189] op_sel_hi:[1,0]
	v_pk_mul_f32 v[20:21], v[20:21], v[188:189] op_sel_hi:[1,0]
	v_pk_mul_f32 v[18:19], v[18:19], v[188:189] op_sel_hi:[1,0]
	v_pk_mul_f32 v[16:17], v[16:17], v[188:189] op_sel_hi:[1,0]
	v_mul_f32_e32 v224, v224, v188
	v_pk_add_f32 v[80:81], v[80:81], v[0:1] op_sel_hi:[1,0] neg_lo:[0,1] neg_hi:[0,1]
	v_pk_add_f32 v[82:83], v[82:83], v[0:1] op_sel_hi:[1,0] neg_lo:[0,1] neg_hi:[0,1]
	v_pk_add_f32 v[84:85], v[84:85], v[0:1] op_sel_hi:[1,0] neg_lo:[0,1] neg_hi:[0,1]
	v_pk_add_f32 v[86:87], v[86:87], v[0:1] op_sel_hi:[1,0] neg_lo:[0,1] neg_hi:[0,1]
	v_pk_add_f32 v[88:89], v[88:89], v[0:1] op_sel_hi:[1,0] neg_lo:[0,1] neg_hi:[0,1]
	v_pk_add_f32 v[90:91], v[90:91], v[0:1] op_sel_hi:[1,0] neg_lo:[0,1] neg_hi:[0,1]
	v_pk_add_f32 v[92:93], v[92:93], v[0:1] op_sel_hi:[1,0] neg_lo:[0,1] neg_hi:[0,1]
	v_pk_add_f32 v[94:95], v[94:95], v[0:1] op_sel_hi:[1,0] neg_lo:[0,1] neg_hi:[0,1]
	v_pk_add_f32 v[96:97], v[96:97], v[0:1] op_sel_hi:[1,0] neg_lo:[0,1] neg_hi:[0,1]
	v_pk_add_f32 v[98:99], v[98:99], v[0:1] op_sel_hi:[1,0] neg_lo:[0,1] neg_hi:[0,1]
	v_pk_add_f32 v[100:101], v[100:101], v[0:1] op_sel_hi:[1,0] neg_lo:[0,1] neg_hi:[0,1]
	v_pk_add_f32 v[102:103], v[102:103], v[0:1] op_sel_hi:[1,0] neg_lo:[0,1] neg_hi:[0,1]
	v_pk_add_f32 v[104:105], v[104:105], v[0:1] op_sel_hi:[1,0] neg_lo:[0,1] neg_hi:[0,1]
	v_pk_add_f32 v[106:107], v[106:107], v[0:1] op_sel_hi:[1,0] neg_lo:[0,1] neg_hi:[0,1]
	v_pk_add_f32 v[108:109], v[108:109], v[0:1] op_sel_hi:[1,0] neg_lo:[0,1] neg_hi:[0,1]
	v_pk_add_f32 v[110:111], v[110:111], v[0:1] op_sel_hi:[1,0] neg_lo:[0,1] neg_hi:[0,1]
	v_add_f32_e32 v2, v2, v0
.LBB0_229:
	v_exp_f32_e32 v80, v80
	v_exp_f32_e32 v81, v81
	v_exp_f32_e32 v82, v82
	v_exp_f32_e32 v83, v83
	v_exp_f32_e32 v84, v84
	v_exp_f32_e32 v85, v85
	v_pk_add_f32 v[188:189], v[80:81], v[82:83]
	v_exp_f32_e32 v86, v86
	v_exp_f32_e32 v87, v87
	v_pk_add_f32 v[188:189], v[188:189], v[84:85]
	v_exp_f32_e32 v88, v88
	v_exp_f32_e32 v89, v89
	v_pk_add_f32 v[188:189], v[188:189], v[86:87]
	v_exp_f32_e32 v90, v90
	v_exp_f32_e32 v91, v91
	v_pk_add_f32 v[188:189], v[188:189], v[88:89]
	v_exp_f32_e32 v92, v92
	v_exp_f32_e32 v93, v93
	v_pk_add_f32 v[188:189], v[188:189], v[90:91]
	v_exp_f32_e32 v94, v94
	v_exp_f32_e32 v95, v95
	v_pk_add_f32 v[188:189], v[188:189], v[92:93]
	v_exp_f32_e32 v96, v96
	v_exp_f32_e32 v97, v97
	v_pk_add_f32 v[188:189], v[188:189], v[94:95]
	v_exp_f32_e32 v98, v98
	v_exp_f32_e32 v99, v99
	v_pk_add_f32 v[188:189], v[188:189], v[96:97]
	v_exp_f32_e32 v100, v100
	v_exp_f32_e32 v101, v101
	v_pk_add_f32 v[188:189], v[188:189], v[98:99]
	v_exp_f32_e32 v102, v102
	v_exp_f32_e32 v103, v103
	v_pk_add_f32 v[188:189], v[188:189], v[100:101]
	v_exp_f32_e32 v104, v104
	v_exp_f32_e32 v105, v105
	v_pk_add_f32 v[188:189], v[188:189], v[102:103]
	v_exp_f32_e32 v106, v106
	v_exp_f32_e32 v107, v107
	v_pk_add_f32 v[188:189], v[188:189], v[104:105]
	v_exp_f32_e32 v108, v108
	v_exp_f32_e32 v109, v109
	v_pk_add_f32 v[188:189], v[188:189], v[106:107]
	v_exp_f32_e32 v110, v110
	v_exp_f32_e32 v111, v111
	v_pk_add_f32 v[188:189], v[188:189], v[108:109]
	s_nop 0
	v_pk_add_f32 v[188:189], v[188:189], v[110:111]
	s_nop 0
	v_add_f32_e32 v0, v188, v189
	v_add_f32_e32 v224, v224, v0
	v_cvt_pk_bf16_f32 v80, v80, v81
	v_cvt_pk_bf16_f32 v81, v82, v83
	v_cvt_pk_bf16_f32 v82, v84, v85
	v_cvt_pk_bf16_f32 v83, v86, v87
	v_cvt_pk_bf16_f32 v88, v88, v89
	v_cvt_pk_bf16_f32 v89, v90, v91
	v_cvt_pk_bf16_f32 v90, v92, v93
	v_cvt_pk_bf16_f32 v91, v94, v95
	v_cvt_pk_bf16_f32 v84, v96, v97
	v_cvt_pk_bf16_f32 v85, v98, v99
	v_cvt_pk_bf16_f32 v86, v100, v101
	v_cvt_pk_bf16_f32 v87, v102, v103
	v_cvt_pk_bf16_f32 v92, v104, v105
	v_cvt_pk_bf16_f32 v93, v106, v107
	v_cvt_pk_bf16_f32 v94, v108, v109
	v_cvt_pk_bf16_f32 v95, v110, v111
	v_add_u32_e32 v0, v14, v152
	ds_read_b128 v[96:99], v0 offset:17408
	ds_read_b128 v[100:103], v0 offset:17440
	ds_read_b128 v[104:107], v0 offset:17472
	ds_read_b128 v[108:111], v0 offset:17504
	s_waitcnt lgkmcnt(11)
	v_mfma_f32_32x32x16_bf16 v[64:79], v[176:179], v[80:83], v[64:79]
	ds_read_b128 v[176:179], v0 offset:26112
	s_waitcnt lgkmcnt(11)
	v_mfma_f32_32x32x16_bf16 v[64:79], v[180:183], v[88:91], v[64:79]
	ds_read_b128 v[180:183], v0 offset:26144
	s_waitcnt lgkmcnt(11)
	v_mfma_f32_32x32x16_bf16 v[64:79], v[184:187], v[84:87], v[64:79]
	ds_read_b128 v[184:187], v0 offset:26176
	s_waitcnt lgkmcnt(11)
	v_mfma_f32_32x32x16_bf16 v[64:79], v[196:199], v[92:95], v[64:79]
	ds_read_b128 v[196:199], v0 offset:26208
	s_waitcnt lgkmcnt(11)
	v_mfma_f32_32x32x16_bf16 v[48:63], v[200:203], v[80:83], v[48:63]
	s_waitcnt lgkmcnt(10)
	v_mfma_f32_32x32x16_bf16 v[48:63], v[204:207], v[88:91], v[48:63]
	s_waitcnt lgkmcnt(9)
	v_mfma_f32_32x32x16_bf16 v[48:63], v[244:247], v[84:87], v[48:63]
	s_waitcnt lgkmcnt(8)
	v_mfma_f32_32x32x16_bf16 v[48:63], v[248:251], v[92:95], v[48:63]
	s_waitcnt lgkmcnt(7)
	v_mfma_f32_32x32x16_bf16 v[32:47], v[96:99], v[80:83], v[32:47]
	s_waitcnt lgkmcnt(6)
	v_mfma_f32_32x32x16_bf16 v[32:47], v[100:103], v[88:91], v[32:47]
	s_waitcnt lgkmcnt(5)
	v_mfma_f32_32x32x16_bf16 v[32:47], v[104:107], v[84:87], v[32:47]
	s_waitcnt lgkmcnt(4)
	v_mfma_f32_32x32x16_bf16 v[32:47], v[108:111], v[92:95], v[32:47]
	s_waitcnt lgkmcnt(3)
	v_mfma_f32_32x32x16_bf16 v[16:31], v[176:179], v[80:83], v[16:31]
	s_waitcnt lgkmcnt(2)
	v_mfma_f32_32x32x16_bf16 v[16:31], v[180:183], v[88:91], v[16:31]
	s_waitcnt lgkmcnt(1)
	v_mfma_f32_32x32x16_bf16 v[16:31], v[184:187], v[84:87], v[16:31]
	s_waitcnt lgkmcnt(0)
	v_mfma_f32_32x32x16_bf16 v[16:31], v[196:199], v[92:95], v[16:31]

; __device__ __forceinline__ void dtile_load(u32x4 (&kr)[2], u32x4 (&vr)[2], const bf16* __restrict__ Kg, const bf16* __restrict__ Vg, int vts, int kt  , int part, int tidx) {
; #pragma unroll
;   for (int i = 0; i < 2; ++i) {
;     const int c = tidx + (2 * part + i) * NTHR;
;     kr[i] = *reinterpret_cast<const u32x4*>(Kg + (size_t)(kt * 128 + (c >> 4)) * 1024 + (c & 15) * 8);
;     vr[i] = *reinterpret_cast<const u32x4*>(Vg + (size_t)(c >> 4) * vts + kt * 128 + (c & 15) * 8);
;   }
; }
; __device__ __forceinline__ void dtile_store(const u32x4 (&kr)[2], const u32x4 (&vr)[2], char* buf, int part, int tidx) {
; #pragma unroll
;   for (int i = 0; i < 2; ++i) {
;     const int c = tidx + (2 * part + i) * NTHR;
;     *reinterpret_cast<u32x4*>(buf + (c >> 4) * KSTR_D + (c & 15) * 16) = kr[i];
;     *reinterpret_cast<u32x4*>(buf + VOFF_D + (c >> 4) * VSTR_D + (c & 15) * 16) = vr[i];
;   }
; }
; __device__ __forceinline__ void attn_diff(const bf16* __restrict__ Qg, const bf16* __restrict__ Kg, const bf16* __restrict__ Vg, int vts, ...
;     ...
;       if (more) { dtile_store(kr, vr, bufn, 1 - hf, tidx); if (hf == 1) dtile_load(kr, vr, Kg, Vg, vts, kt2 - 1, 1, tidx); }
.LBB0_231:
	s_or_b64 exec, exec, s[90:91]
	s_and_saveexec_b64 s[12:13], s[10:11]
	s_cbranch_execz .LBB0_222
	v_add_u32_e32 v0, s84, v150
	v_lshrrev_b32_e32 v80, 4, v0
	v_add_u32_e32 v0, 0x200, v0
	v_mad_u64_u32 v[80:81], s[14:15], v80, s33, v[4:5]
	v_lshrrev_b32_e32 v0, 4, v0
	s_waitcnt vmcnt(0) lgkmcnt(0)
	ds_write_b128 v80, v[128:131]
	ds_write_b128 v80, v[132:135] offset:34816
	v_mad_u64_u32 v[80:81], s[14:15], v0, s33, v[4:5]
	s_cmp_lg_u32 s84, 0
	ds_write_b128 v80, v[136:139]
	ds_write_b128 v80, v[140:143] offset:34816
	s_cbranch_scc1 .LBB0_222
	global_load_dwordx4 v[128:131], v[6:7], off
	global_load_dwordx4 v[132:135], v[8:9], off
	global_load_dwordx4 v[136:139], v[10:11], off
	global_load_dwordx4 v[140:143], v[12:13], off
	s_branch .LBB0_222

;   __device__ __forceinline__ const float* in(int i) const { return reinterpret_cast<const float*>(ld64(i * 8)); }
;   __device__ __forceinline__ unsigned char* ws() const { return reinterpret_cast<unsigned char*>(ld64(27 * 8)); }
; __device__ __forceinline__ int opaque_tid() { int t = threadIdx.x; asm volatile("" : "+v"(t)); return t; }
; __device__ __forceinline__ void phase_cache(const PRef& p, char* lds) {
;   const int tidx = opaque_tid();
;   bf16* ks = (bf16*)(p.ws() + WS_KS);
;   bf16* vts = (bf16*)(p.ws() + WS_VTS);
;   const float* c_sbk = p.in(2); const float* c_sbv = p.in(3); const float* c_dk = p.in(4); const float* c_dv = p.in(5);
;   const int gtid = blockIdx.x * NTHR + tidx, gsz = gridDim.x * NTHR;
;   for (int u = gtid; u < 8 * PAST * 256; u += gsz) {
;     int c4 = u & 255, pos = (u >> 8) & (PAST - 1), b = u >> 19;
.LBB0_284:
	s_and_b64 vcc, exec, s[0:1]
	s_cbranch_vccz .LBB0_302
	v_readlane_b32 s4, v254, 10
	s_cmp_gt_i32 s4, 2
	s_mov_b64 s[0:1], -1
	v_readlane_b32 s5, v254, 11
	s_cbranch_scc0 .LBB0_314
	s_cmp_gt_i32 s4, 3
	s_cbranch_scc0 .LBB0_304
	v_readlane_b32 s0, v254, 5
	s_mov_b64 s[4:5], src_shared_base
	s_cmp_lg_u32 s0, -1
	s_cselect_b32 s0, s0, 0
	s_cselect_b32 s1, s5, 0
	v_mov_b32_e32 v20, v171
	v_mov_b64_e32 v[2:3], s[0:1]
	v_readlane_b32 s0, v254, 6
	flat_load_dword v0, v[2:3] sc0 sc1
	s_waitcnt vmcnt(0)
	s_cmp_lg_u32 s0, -1
	s_cselect_b32 s0, s0, 0
	s_cselect_b32 s1, s5, 0
	v_mov_b64_e32 v[4:5], s[0:1]
	flat_load_dword v6, v[4:5] sc0 sc1
	s_waitcnt vmcnt(0)
	flat_load_dword v7, v[2:3] sc0 sc1
	s_waitcnt vmcnt(0)
	flat_load_dword v4, v[4:5] sc0 sc1
	s_waitcnt vmcnt(0) lgkmcnt(0)
	v_readfirstlane_b32 s0, v0
	s_add_u32 s0, s0, 0xcd00000
	v_readfirstlane_b32 s1, v6
	s_addc_u32 s1, s1, 0
	s_add_i32 s4, 0, 0x23f10
	s_cmp_lg_u32 s4, -1
	s_cselect_b32 s4, s4, 0
	s_cselect_b32 s6, s5, 0
	s_add_i32 s7, 0, 0x23f14
	s_cmp_lg_u32 s7, -1
	v_mov_b32_e32 v2, s4
	v_mov_b32_e32 v3, s6
	s_cselect_b32 s4, s7, 0
	s_cselect_b32 s6, s5, 0
	s_add_i32 s7, 0, 0x23f18
	s_cmp_lg_u32 s7, -1
	flat_load_dword v0, v[2:3] sc0 sc1
	s_waitcnt vmcnt(0)
	v_mov_b32_e32 v2, s4
	v_mov_b32_e32 v3, s6
	s_cselect_b32 s4, s7, 0
	s_cselect_b32 s6, s5, 0
	s_add_i32 s7, 0, 0x23f1c
	s_cmp_lg_u32 s7, -1
	flat_load_dword v5, v[2:3] sc0 sc1
	s_waitcnt vmcnt(0)
	v_mov_b32_e32 v2, s4
	v_mov_b32_e32 v3, s6
	s_cselect_b32 s4, s7, 0
	s_cselect_b32 s6, s5, 0
	s_add_i32 s7, 0, 0x23f20
	s_cmp_lg_u32 s7, -1
	flat_load_dword v6, v[2:3] sc0 sc1
	s_waitcnt vmcnt(0)
	v_mov_b32_e32 v2, s4
	v_mov_b32_e32 v3, s6
	s_cselect_b32 s4, s7, 0
	s_cselect_b32 s6, s5, 0
	s_add_i32 s7, 0, 0x23f24
	s_cmp_lg_u32 s7, -1
	flat_load_dword v9, v[2:3] sc0 sc1
	s_waitcnt vmcnt(0)
	v_mov_b32_e32 v2, s4
	v_mov_b32_e32 v3, s6
	s_cselect_b32 s4, s7, 0
	s_cselect_b32 s6, s5, 0
	s_add_i32 s7, 0, 0x23f28
	s_cmp_lg_u32 s7, -1
	flat_load_dword v10, v[2:3] sc0 sc1
	s_waitcnt vmcnt(0)
	v_mov_b32_e32 v2, s4
	v_mov_b32_e32 v3, s6
	s_cselect_b32 s4, s7, 0
	s_cselect_b32 s6, s5, 0
	s_add_i32 s7, 0, 0x23f2c
	s_cmp_lg_u32 s7, -1
	flat_load_dword v11, v[2:3] sc0 sc1
	s_waitcnt vmcnt(0)
	v_mov_b32_e32 v2, s4
	v_mov_b32_e32 v3, s6
	s_cselect_b32 s4, s7, 0
	s_cselect_b32 s5, s5, 0
	flat_load_dword v12, v[2:3] sc0 sc1
	s_waitcnt vmcnt(0)
	v_mov_b32_e32 v2, s4
	v_mov_b32_e32 v3, s5
	flat_load_dword v2, v[2:3] sc0 sc1
	s_waitcnt vmcnt(0)
	v_readlane_b32 s4, v254, 13
	v_readfirstlane_b32 s14, v7
	v_readfirstlane_b32 s15, v4
	v_add_u32_e32 v8, s4, v20
	s_mov_b32 s4, 0x400000
	v_cmp_gt_i32_e32 vcc, s4, v8
	s_waitcnt lgkmcnt(0)
	v_readfirstlane_b32 s6, v0
	v_readfirstlane_b32 s7, v5
	v_readfirstlane_b32 s10, v6
	v_readfirstlane_b32 s11, v9
	v_readfirstlane_b32 s8, v10
	v_readfirstlane_b32 s9, v11
	v_readfirstlane_b32 s12, v12
	v_readfirstlane_b32 s13, v2
	s_and_saveexec_b64 s[4:5], vcc
	s_movk_i32 s18, 0x840
	s_cbranch_execz .LBB0_290
	v_mov_b32_e32 v0, 4
	v_lshlrev_b32_sdwa v0, v0, v20 dst_sel:DWORD dst_unused:UNUSED_PAD src0_sel:DWORD src1_sel:BYTE_0
	v_lshl_add_u64 v[2:3], s[8:9], 0, v[0:1]
	v_lshl_add_u64 v[4:5], s[6:7], 0, v[0:1]
	v_mov_b32_e32 v0, 3
	s_movk_i32 s16, 0x80
	v_lshlrev_b32_sdwa v0, v0, v20 dst_sel:DWORD dst_unused:UNUSED_PAD src0_sel:DWORD src1_sel:BYTE_0
	v_cmp_lt_u32_sdwa vcc, v20, s16 src0_sel:BYTE_0 src1_sel:DWORD
	v_lshl_add_u64 v[6:7], s[0:1], 0, v[0:1]
	s_mov_b64 s[8:9], 0
	v_mov_b32_e32 v0, v8
	s_mov_b64 s[24:25], vcc
	s_movk_i32 s6, 0xf800
	s_mov_b32 s7, -1
	v_lshl_add_u64 v[42:43], v[2:3], 0, s[6:7]
	v_cndmask_b32_e32 v43, v43, v5, vcc
	v_cndmask_b32_e32 v42, v42, v4, vcc
	s_mul_i32 s19, s48, 7
	s_lshl_b32 s20, s48, 3
	s_mov_b32 s21, 0x400000
	s_mov_b64 s[26:27], exec
; __device__ __forceinline__ void phase_cache(const PRef& p, char* lds) {
;     ...
;   for (int u = gtid; u < 8 * PAST * 256; u += gsz) {
;     int c4 = u & 255, pos = (u >> 8) & (PAST - 1), b = u >> 19;
;     const float* src = (c4 < 128) ? c_sbk + ((size_t)(b * PAST + pos) * 512 + c4 * 4) : c_dk + ((size_t)(b * PAST + pos) * 512 + (c4 - 128) * 4);
;     const f32x4v v = __builtin_nontemporal_load(reinterpret_cast<const f32x4v*>(src));
;     u32x2 w = {cvtpk(v[0], v[1]), cvtpk(v[2], v[3])};
;     *reinterpret_cast<u32x2*>(ks + ((size_t)(b * SPAD + pos) * 1024 + c4 * 4)) = w;
;   }
.Lmy_k8:
	v_add_u32_e32 v44, s19, v0
	v_cmp_gt_i32_e32 vcc, s21, v44
	s_and_b64 exec, exec, vcc
	s_cbranch_execz .Lmy_k8_done
	v_mov_b32_e32 v44, v0
	v_bfe_u32 v46, v44, 8, 11
	v_ashrrev_i32_e32 v47, 19, v44
	v_lshl_or_b32 v48, v47, 11, v46
	v_ashrrev_i32_e32 v49, 31, v48
	v_lshlrev_b64 v[48:49], 11, v[48:49]
	v_lshl_add_u64 v[50:51], v[42:43], 0, v[48:49]
	global_load_dwordx4 v[52:55], v[50:51], off nt
	v_mad_i32_i24 v56, v47, s18, v46
	v_ashrrev_i32_e32 v57, 31, v56
	v_lshlrev_b64 v[56:57], 11, v[56:57]
	v_lshl_add_u64 v[56:57], v[6:7], 0, v[56:57]
	v_add_u32_e32 v44, s48, v44
	v_bfe_u32 v58, v44, 8, 11
	v_ashrrev_i32_e32 v59, 19, v44
	v_lshl_or_b32 v60, v59, 11, v58
	v_ashrrev_i32_e32 v61, 31, v60
	v_lshlrev_b64 v[60:61], 11, v[60:61]
	v_lshl_add_u64 v[62:63], v[42:43], 0, v[60:61]
	global_load_dwordx4 v[64:67], v[62:63], off nt
	v_mad_i32_i24 v68, v59, s18, v58
	v_ashrrev_i32_e32 v69, 31, v68
	v_lshlrev_b64 v[68:69], 11, v[68:69]
	v_lshl_add_u64 v[68:69], v[6:7], 0, v[68:69]
	v_add_u32_e32 v44, s48, v44
	v_bfe_u32 v70, v44, 8, 11
	v_ashrrev_i32_e32 v71, 19, v44
	v_lshl_or_b32 v72, v71, 11, v70
	v_ashrrev_i32_e32 v73, 31, v72
	v_lshlrev_b64 v[72:73], 11, v[72:73]
	v_lshl_add_u64 v[74:75], v[42:43], 0, v[72:73]
	global_load_dwordx4 v[76:79], v[74:75], off nt
	v_mad_i32_i24 v80, v71, s18, v70
	v_ashrrev_i32_e32 v81, 31, v80
	v_lshlrev_b64 v[80:81], 11, v[80:81]
	v_lshl_add_u64 v[80:81], v[6:7], 0, v[80:81]
	v_add_u32_e32 v44, s48, v44
	v_bfe_u32 v82, v44, 8, 11
	v_ashrrev_i32_e32 v83, 19, v44
	v_lshl_or_b32 v84, v83, 11, v82
	v_ashrrev_i32_e32 v85, 31, v84
	v_lshlrev_b64 v[84:85], 11, v[84:85]
	v_lshl_add_u64 v[86:87], v[42:43], 0, v[84:85]
	global_load_dwordx4 v[88:91], v[86:87], off nt
	v_mad_i32_i24 v92, v83, s18, v82
	v_ashrrev_i32_e32 v93, 31, v92
	v_lshlrev_b64 v[92:93], 11, v[92:93]
	v_lshl_add_u64 v[92:93], v[6:7], 0, v[92:93]
	v_add_u32_e32 v44, s48, v44
	v_bfe_u32 v94, v44, 8, 11
	v_ashrrev_i32_e32 v95, 19, v44
	v_lshl_or_b32 v96, v95, 11, v94
	v_ashrrev_i32_e32 v97, 31, v96
	v_lshlrev_b64 v[96:97], 11, v[96:97]
	v_lshl_add_u64 v[98:99], v[42:43], 0, v[96:97]
	global_load_dwordx4 v[100:103], v[98:99], off nt
	v_mad_i32_i24 v104, v95, s18, v94
	v_ashrrev_i32_e32 v105, 31, v104
	v_lshlrev_b64 v[104:105], 11, v[104:105]
	v_lshl_add_u64 v[104:105], v[6:7], 0, v[104:105]
	v_add_u32_e32 v44, s48, v44
	v_bfe_u32 v106, v44, 8, 11
	v_ashrrev_i32_e32 v107, 19, v44
	v_lshl_or_b32 v108, v107, 11, v106
	v_ashrrev_i32_e32 v109, 31, v108
	v_lshlrev_b64 v[108:109], 11, v[108:109]
	v_lshl_add_u64 v[110:111], v[42:43], 0, v[108:109]
	global_load_dwordx4 v[112:115], v[110:111], off nt
	v_mad_i32_i24 v116, v107, s18, v106
	v_ashrrev_i32_e32 v117, 31, v116
	v_lshlrev_b64 v[116:117], 11, v[116:117]
	v_lshl_add_u64 v[116:117], v[6:7], 0, v[116:117]
	v_add_u32_e32 v44, s48, v44
	v_bfe_u32 v118, v44, 8, 11
	v_ashrrev_i32_e32 v119, 19, v44
	v_lshl_or_b32 v120, v119, 11, v118
	v_ashrrev_i32_e32 v121, 31, v120
	v_lshlrev_b64 v[120:121], 11, v[120:121]
	v_lshl_add_u64 v[122:123], v[42:43], 0, v[120:121]
	global_load_dwordx4 v[124:127], v[122:123], off nt
	v_mad_i32_i24 v128, v119, s18, v118
	v_ashrrev_i32_e32 v129, 31, v128
	v_lshlrev_b64 v[128:129], 11, v[128:129]
	v_lshl_add_u64 v[128:129], v[6:7], 0, v[128:129]
	v_add_u32_e32 v44, s48, v44
	v_bfe_u32 v130, v44, 8, 11
	v_ashrrev_i32_e32 v131, 19, v44
	v_lshl_or_b32 v132, v131, 11, v130
	v_ashrrev_i32_e32 v133, 31, v132
	v_lshlrev_b64 v[132:133], 11, v[132:133]
	v_lshl_add_u64 v[134:135], v[42:43], 0, v[132:133]
	global_load_dwordx4 v[136:139], v[134:135], off nt
	v_mad_i32_i24 v140, v131, s18, v130
	v_ashrrev_i32_e32 v141, 31, v140
	v_lshlrev_b64 v[140:141], 11, v[140:141]
	v_lshl_add_u64 v[140:141], v[6:7], 0, v[140:141]
	v_add_u32_e32 v44, s48, v44
	s_waitcnt vmcnt(7)
	v_cvt_pk_bf16_f32 v52, v52, v53
	v_cvt_pk_bf16_f32 v53, v54, v55
	global_store_dwordx2 v[56:57], v[52:53], off
	s_waitcnt vmcnt(7)
	v_cvt_pk_bf16_f32 v64, v64, v65
	v_cvt_pk_bf16_f32 v65, v66, v67
	global_store_dwordx2 v[68:69], v[64:65], off
	s_waitcnt vmcnt(7)
	v_cvt_pk_bf16_f32 v76, v76, v77
	v_cvt_pk_bf16_f32 v77, v78, v79
	global_store_dwordx2 v[80:81], v[76:77], off
	s_waitcnt vmcnt(7)
	v_cvt_pk_bf16_f32 v88, v88, v89
	v_cvt_pk_bf16_f32 v89, v90, v91
	global_store_dwordx2 v[92:93], v[88:89], off
	s_waitcnt vmcnt(7)
	v_cvt_pk_bf16_f32 v100, v100, v101
	v_cvt_pk_bf16_f32 v101, v102, v103
	global_store_dwordx2 v[104:105], v[100:101], off
	s_waitcnt vmcnt(7)
	v_cvt_pk_bf16_f32 v112, v112, v113
	v_cvt_pk_bf16_f32 v113, v114, v115
	global_store_dwordx2 v[116:117], v[112:113], off
	s_waitcnt vmcnt(7)
	v_cvt_pk_bf16_f32 v124, v124, v125
	v_cvt_pk_bf16_f32 v125, v126, v127
	global_store_dwordx2 v[128:129], v[124:125], off
	s_waitcnt vmcnt(7)
	v_cvt_pk_bf16_f32 v136, v136, v137
	v_cvt_pk_bf16_f32 v137, v138, v139
	global_store_dwordx2 v[140:141], v[136:137], off
	v_add_u32_e32 v0, s20, v0
	s_branch .Lmy_k8
.Lmy_k8_done:
	s_mov_b64 exec, s[26:27]
	v_cmp_gt_i32_e32 vcc, s21, v0
	s_and_b64 exec, exec, vcc
	s_cbranch_execz .LBB0_290
	s_mov_b64 vcc, s[24:25]

; __device__ __forceinline__ void phase_cache(const PRef& p, char* lds) {
;     ...
;   for (int u = blockIdx.x; u < 8 * 32 * 4; u += gridDim.x) {
;     const int rb = u & 3, pb = (u >> 2) & 31, b = u >> 7;
;     const int r0 = rb * 256, p0 = pb * 64;
;     const float* src = (r0 < 512) ? c_sbv + (size_t)(b * PAST + p0) * 512 + r0 : c_dv + (size_t)(b * PAST + p0) * 512 + (r0 - 512);
;     __syncthreads();
; #pragma unroll
;     for (int pp = 0; pp < 4; ++pp) {
;       const int pr = wv * 4 + pp;
;       float a[4], c[4];
; #pragma unroll
;       for (int i = 0; i < 4; ++i) { a[i] = __builtin_nontemporal_load(src + (size_t)(2 * pr) * 512 + lane + 64 * i); c[i] = __builtin_nontemporal_load(src + (size_t)(2 * pr + 1) * 512 + lane + 64 * i); }
; #pragma unroll
;       for (int i = 0; i < 4; ++i) tl[(lane + 64 * i) * 33 + pr] = cvtpk(a[i], c[i]);
;     }
;     __syncthreads();
; #pragma unroll
;     for (int q = 0; q < 2; ++q) {
;       const int id = tidx + q * NTHR, r = id >> 2, c = id & 3;
;       unsigned d[8];
; #pragma unroll
;       for (int k = 0; k < 8; ++k) d[k] = tl[r * 33 + c * 8 + k];
;       u32x4 w0 = {d[0], d[1], d[4], d[5]}, w1 = {d[2], d[3], d[6], d[7]};
;       bf16* dst = vts + (size_t)(b * 1024 + r0 + r) * SPAD + p0 + c * 16;
;       *reinterpret_cast<u32x4*>(dst) = w0; *reinterpret_cast<u32x4*>(dst + 8) = w1;
.LBB0_297:
	v_lshl_add_u64 v[26:27], s[0:1], 0, v[0:1]
	v_lshl_add_u64 v[150:151], v[26:27], 0, v[6:7]
	v_lshl_add_u64 v[152:153], v[26:27], 0, v[4:5]
	v_lshl_add_u64 v[154:155], v[26:27], 0, v[10:11]
	v_lshl_add_u64 v[156:157], v[26:27], 0, v[8:9]
	v_lshl_add_u64 v[158:159], v[26:27], 0, v[14:15]
	v_lshl_add_u64 v[160:161], v[26:27], 0, v[12:13]
	v_lshl_add_u64 v[162:163], v[26:27], 0, v[18:19]
	v_lshl_add_u64 v[164:165], v[26:27], 0, v[16:17]
	global_load_dword v100, v[150:151], off nt
	global_load_dword v101, v[152:153], off nt
	global_load_dword v102, v[150:151], off offset:256 nt
	global_load_dword v103, v[152:153], off offset:256 nt
	global_load_dword v104, v[150:151], off offset:512 nt
	global_load_dword v105, v[152:153], off offset:512 nt
	global_load_dword v106, v[150:151], off offset:768 nt
	global_load_dword v107, v[152:153], off offset:768 nt
	global_load_dword v108, v[154:155], off nt
	global_load_dword v109, v[156:157], off nt
	global_load_dword v110, v[154:155], off offset:256 nt
	global_load_dword v111, v[156:157], off offset:256 nt
	global_load_dword v112, v[154:155], off offset:512 nt
	global_load_dword v113, v[156:157], off offset:512 nt
	global_load_dword v114, v[154:155], off offset:768 nt
	global_load_dword v115, v[156:157], off offset:768 nt
	global_load_dword v116, v[158:159], off nt
	global_load_dword v117, v[160:161], off nt
	global_load_dword v118, v[158:159], off offset:256 nt
	global_load_dword v119, v[160:161], off offset:256 nt
	global_load_dword v120, v[158:159], off offset:512 nt
	global_load_dword v121, v[160:161], off offset:512 nt
	global_load_dword v122, v[158:159], off offset:768 nt
	global_load_dword v123, v[160:161], off offset:768 nt
	global_load_dword v124, v[162:163], off nt
	global_load_dword v125, v[164:165], off nt
	global_load_dword v126, v[162:163], off offset:256 nt
	global_load_dword v127, v[164:165], off offset:256 nt
	global_load_dword v128, v[162:163], off offset:512 nt
	global_load_dword v129, v[164:165], off offset:512 nt
	global_load_dword v130, v[162:163], off offset:768 nt
	global_load_dword v131, v[164:165], off offset:768 nt
	s_waitcnt lgkmcnt(0)
	s_barrier
	s_lshl_b32 s0, s16, 10
	s_lshl_b32 s86, s17, 1
	v_readlane_b32 s1, v254, 38
	s_or_b32 s0, s0, s15
	s_add_i32 s9, s9, s1
	v_readlane_b32 s1, v254, 39
	s_add_i32 s8, s8, s1
	v_readlane_b32 s4, v254, 1
	s_add_i32 s14, s14, s4
	s_cmpk_lt_i32 s14, 0x400
	v_readlane_b32 s5, v254, 2
	v_add_u32_e32 v39, s0, v21
	v_lshl_add_u64 v[34:35], v[2:3], 0, s[86:87]
	s_waitcnt vmcnt(24)
	v_cvt_pk_bf16_f32 v32, v101, v100
	ds_write_b32 v22, v32
	v_cvt_pk_bf16_f32 v32, v103, v102
	ds_write_b32 v22, v32 offset:8448
	v_cvt_pk_bf16_f32 v32, v105, v104
	ds_write_b32 v22, v32 offset:16896
	v_cvt_pk_bf16_f32 v32, v107, v106
	ds_write_b32 v22, v32 offset:25344
	s_waitcnt vmcnt(16)
	v_cvt_pk_bf16_f32 v32, v109, v108
	ds_write_b32 v22, v32 offset:4
	v_cvt_pk_bf16_f32 v32, v111, v110
	ds_write_b32 v22, v32 offset:8452
	v_cvt_pk_bf16_f32 v32, v113, v112
	ds_write_b32 v22, v32 offset:16900
	v_cvt_pk_bf16_f32 v32, v115, v114
	ds_write_b32 v22, v32 offset:25348
	s_waitcnt vmcnt(8)
	v_cvt_pk_bf16_f32 v32, v117, v116
	ds_write_b32 v22, v32 offset:8
	v_cvt_pk_bf16_f32 v32, v119, v118
	ds_write_b32 v22, v32 offset:8456
	v_cvt_pk_bf16_f32 v32, v121, v120
	ds_write_b32 v22, v32 offset:16904
	v_cvt_pk_bf16_f32 v32, v123, v122
	ds_write_b32 v22, v32 offset:25352
	s_waitcnt vmcnt(0)
	v_cvt_pk_bf16_f32 v32, v125, v124
	ds_write_b32 v23, v32
	v_cvt_pk_bf16_f32 v32, v127, v126
	ds_write_b32 v23, v32 offset:8448
	v_cvt_pk_bf16_f32 v32, v129, v128
	ds_write_b32 v23, v32 offset:16896
	v_cvt_pk_bf16_f32 v32, v131, v130
	ds_write_b32 v23, v32 offset:25344
	s_waitcnt lgkmcnt(0)
	s_barrier
	ds_read2_b32 v[26:27], v24 offset1:1
	ds_read2_b32 v[30:31], v24 offset0:2 offset1:3
	ds_read2_b32 v[28:29], v24 offset0:4 offset1:5
	ds_read2_b32 v[32:33], v24 offset0:6 offset1:7
	v_add_u32_e32 v38, s0, v20
	v_mad_i64_i32 v[36:37], s[0:1], v39, s50, v[34:35]
	s_waitcnt lgkmcnt(1)
	flat_store_dwordx4 v[36:37], v[26:29]
	s_waitcnt lgkmcnt(0)
	flat_store_dwordx4 v[36:37], v[30:33] offset:16
	ds_read2_b32 v[26:27], v25 offset1:1
	ds_read2_b32 v[30:31], v25 offset0:2 offset1:3
	ds_read2_b32 v[28:29], v25 offset0:4 offset1:5
	ds_read2_b32 v[32:33], v25 offset0:6 offset1:7
	v_mad_i64_i32 v[34:35], s[0:1], v38, s50, v[34:35]
	s_waitcnt lgkmcnt(0)
	flat_store_dwordx4 v[34:35], v[26:29]
	flat_store_dwordx4 v[34:35], v[30:33] offset:16
	s_cbranch_scc0 .LBB0_303
